# GEMM K-loop: per-iteration tile-pointer bookkeeping moved from the top of the load segment to behind the last MFMA block of the previous iteration
# baseline (speedup 1.0000x reference)
; #define PG8_STAGE(bufoff, gbase, voff) do { _Pragma("unroll") for (int _i = 0; _i < 2; ++_i) \
;         __builtin_amdgcn_global_load_lds((const unsigned*)((const char*)(gbase) + (voff)[_i]), (PG8_LAS unsigned*)(lds + (bufoff) + ldsw + _i * 8192), 16, 0, 0); } while (0)
; #define PG8_LDA(dst, b, h) do { _Pragma("unroll") for (int m = 0; m < 4; ++m) _Pragma("unroll") for (int k = 0; k < 2; ++k) dst[m][k] = *(const PG8_LAS bf16x8*)(lds + PG8_SA(b, h) + aoff + m * 2048 + k * 1024); } while (0)
; #define PG8_LDB(dst, b, h) do { _Pragma("unroll") for (int n = 0; n < 2; ++n) _Pragma("unroll") for (int k = 0; k < 2; ++k) dst[n][k] = *(const PG8_LAS bf16x8*)(lds + PG8_SB(b, h) + boff + n * 2048 + k * 1024); } while (0)
; #define PG8_MMA(ai, bj, At, Bt) do { __builtin_amdgcn_s_setprio(1); _Pragma("unroll") for (int m = 0; m < 4; ++m) _Pragma("unroll") for (int n = 0; n < 2; ++n) _Pragma("unroll") for (int k = 0; k < 2; ++k) \
;         acc[ai][bj][m][n] = __builtin_amdgcn_mfma_f32_16x16x32_bf16(Bt[n][k], At[m][k], acc[ai][bj][m][n], 0, 0, 0); __builtin_amdgcn_s_setprio(0); } while (0)
; #define PG8_WAIT_V(n) asm volatile("s_waitcnt vmcnt(" #n ")" ::: "memory")
; #define PG8_BAR __builtin_amdgcn_s_barrier()
; template <class Epi, class Sched, bool ALIGN_EPI = false, bool SP2 = false>
; __device__ __forceinline__ void gemm_phase(PG8_LAS unsigned char* lds, const Gemm g, const Sched& S, const Epi& E, const int tid_in) {
;     ...
;         for (int t = 0; t < nt; t += 2) {
;             const bool last = (t == nt - 2);
;             const char* a1 = cA + (size_t)(t + 1) * kstep;
;             const char* a2 = last ? nA : cA + (size_t)(t + 2) * kstep; const char* b2 = last ? nB : cB + (size_t)(t + 2) * kstep;
;             const char* a3 = a2 + kstep; const char* b3 = b2 + kstep;
;             if (last && has_next) S.a_ready(nxt);
;             if constexpr (SP2) {
;             PG8_LDB(B0, 0, 0); PG8_LDB(B1, 0, 1); PG8_SCHED; PG8_LDA(At, 0, 0); PG8_STAGE(PG8_SA(1, 1), a1 + hstep, voffA);
;             PG8_WAIT_V(8); PG8_WAIT_L(0); PG8_BAR; PG8_MMA(0, 0, At, B0); PG8_MMA(0, 1, At, B1); PG8_BAR; PG8_SCHED;
;             PG8_LDA(At, 0, 1); PG8_STAGE(PG8_SB(0, 0), b2, voffB); PG8_STAGE(PG8_SB(0, 1), b2 + hstep, voffB); PG8_STAGE(PG8_SA(0, 0), a2, voffA);
;             PG8_WAIT_V(8); PG8_WAIT_L(0); PG8_BAR; PG8_MMA(1, 0, At, B0); PG8_MMA(1, 1, At, B1); PG8_BAR; PG8_SCHED;
.LBB0_114:
	s_mov_b32 s52, 0
	s_mov_b64 s[10:11], 0x100
	v_mov_b64_e32 v[130:131], v[172:173]
	v_mov_b64_e32 v[132:133], v[170:171]
	s_add_u32 vcc_lo, s2, s10
	s_addc_u32 s53, s3, s11
	s_add_u32 s44, s50, s10
	s_addc_u32 s45, s51, s11
	s_cmp_eq_u32 s68, 0
	s_cselect_b32 s53, s49, s53
	s_cselect_b32 s52, s48, vcc_lo
	s_cselect_b32 vcc_hi, s43, s45
	s_cselect_b32 vcc_lo, s42, s44
	s_add_u32 s98, vcc_lo, 0x80
	s_addc_u32 s99, vcc_hi, 0
	s_add_u32 s100, s52, 0x80
	s_addc_u32 s101, s53, 0
	s_mov_b32 s77, 0
.LBB0_115:
	s_add_i32 s77, s77, 2
	s_add_i32 s16, 0, 0x10000
	v_add_u32_e32 v0, s16, v177
	s_add_i32 s17, 0, 0x14000
	ds_read_b128 v[134:137], v0
	ds_read_b128 v[138:141], v0 offset:1024
	ds_read_b128 v[142:145], v0 offset:2048
	ds_read_b128 v[146:149], v0 offset:3072
	v_add_u32_e32 v0, s17, v177
	ds_read_b128 v[150:153], v0
	ds_read_b128 v[154:157], v0 offset:1024
	ds_read_b128 v[158:161], v0 offset:2048
	ds_read_b128 v[180:183], v0 offset:3072
	s_add_i32 m0, s60, 0xc000
	ds_read_b128 v[184:187], v179
	ds_read_b128 v[188:191], v179 offset:1024
	ds_read_b128 v[192:195], v179 offset:2048
	ds_read_b128 v[196:199], v179 offset:3072
	ds_read_b128 v[200:203], v179 offset:4096
	ds_read_b128 v[204:207], v179 offset:5120
	ds_read_b128 v[208:211], v179 offset:6144
	ds_read_b128 v[212:215], v179 offset:7168
	global_load_lds_dwordx4 v132, s[2:3]
	s_add_i32 m0, s60, 0xe000
	s_nop 0
	global_load_lds_dwordx4 v130, s[2:3]
	s_waitcnt vmcnt(8)
	s_waitcnt lgkmcnt(0)
	s_barrier
	s_setprio 1
	s_waitcnt lgkmcnt(0)
	v_mfma_f32_16x16x32_bf16 v[126:129], v[134:137], v[184:187], v[126:129]
	v_mfma_f32_16x16x32_bf16 v[122:125], v[142:145], v[184:187], v[122:125]
	v_mfma_f32_16x16x32_bf16 v[110:113], v[134:137], v[192:195], v[110:113]
	v_mfma_f32_16x16x32_bf16 v[106:109], v[142:145], v[192:195], v[106:109]
	v_mfma_f32_16x16x32_bf16 v[94:97], v[134:137], v[200:203], v[94:97]
	v_mfma_f32_16x16x32_bf16 v[90:93], v[142:145], v[200:203], v[90:93]
	v_mfma_f32_16x16x32_bf16 v[78:81], v[134:137], v[208:211], v[78:81]
	v_mfma_f32_16x16x32_bf16 v[74:77], v[142:145], v[208:211], v[74:77]
	v_mfma_f32_16x16x32_bf16 v[126:129], v[138:141], v[188:191], v[126:129]
	v_mfma_f32_16x16x32_bf16 v[122:125], v[146:149], v[188:191], v[122:125]
	v_mfma_f32_16x16x32_bf16 v[110:113], v[138:141], v[196:199], v[110:113]
	v_mfma_f32_16x16x32_bf16 v[106:109], v[146:149], v[196:199], v[106:109]
	v_mfma_f32_16x16x32_bf16 v[94:97], v[138:141], v[204:207], v[94:97]
	v_mfma_f32_16x16x32_bf16 v[90:93], v[146:149], v[204:207], v[90:93]
	v_mfma_f32_16x16x32_bf16 v[78:81], v[138:141], v[212:215], v[78:81]
	v_mfma_f32_16x16x32_bf16 v[74:77], v[146:149], v[212:215], v[74:77]
	s_setprio 0
	s_setprio 1
	v_mfma_f32_16x16x32_bf16 v[118:121], v[150:153], v[184:187], v[118:121]
	v_mfma_f32_16x16x32_bf16 v[114:117], v[158:161], v[184:187], v[114:117]
	v_mfma_f32_16x16x32_bf16 v[102:105], v[150:153], v[192:195], v[102:105]
	v_mfma_f32_16x16x32_bf16 v[98:101], v[158:161], v[192:195], v[98:101]
	v_mfma_f32_16x16x32_bf16 v[86:89], v[150:153], v[200:203], v[86:89]
	v_mfma_f32_16x16x32_bf16 v[82:85], v[158:161], v[200:203], v[82:85]
	v_mfma_f32_16x16x32_bf16 v[70:73], v[150:153], v[208:211], v[70:73]
	v_mfma_f32_16x16x32_bf16 v[66:69], v[158:161], v[208:211], v[66:69]
	v_mfma_f32_16x16x32_bf16 v[118:121], v[154:157], v[188:191], v[118:121]
	v_mfma_f32_16x16x32_bf16 v[114:117], v[180:183], v[188:191], v[114:117]
	v_mfma_f32_16x16x32_bf16 v[102:105], v[154:157], v[196:199], v[102:105]
	v_mfma_f32_16x16x32_bf16 v[98:101], v[180:183], v[196:199], v[98:101]
	v_mfma_f32_16x16x32_bf16 v[86:89], v[154:157], v[204:207], v[86:89]
	v_mfma_f32_16x16x32_bf16 v[82:85], v[180:183], v[204:207], v[82:85]
	v_mfma_f32_16x16x32_bf16 v[70:73], v[154:157], v[212:215], v[70:73]
	v_mfma_f32_16x16x32_bf16 v[66:69], v[180:183], v[212:215], v[66:69]
	s_setprio 0
	s_barrier
	s_add_i32 s16, s16, s59
	s_mov_b32 m0, s16
	ds_read_b128 v[184:187], v179 offset:16384
	ds_read_b128 v[188:191], v179 offset:17408
	ds_read_b128 v[192:195], v179 offset:18432
	ds_read_b128 v[196:199], v179 offset:19456
	ds_read_b128 v[200:203], v179 offset:20480
	ds_read_b128 v[204:207], v179 offset:21504
	ds_read_b128 v[208:211], v179 offset:22528
	ds_read_b128 v[212:215], v179 offset:23552
	global_load_lds_dwordx4 v164, vcc
	s_add_i32 m0, s16, 0x2000
	s_add_i32 s16, s17, s59
	global_load_lds_dwordx4 v168, vcc
	s_add_u32 vcc_lo, vcc_lo, s82
	s_addc_u32 vcc_hi, vcc_hi, 0
	s_mov_b32 m0, s16
	s_nop 0
	global_load_lds_dwordx4 v164, vcc
	s_add_i32 m0, s16, 0x2000
	s_nop 0
	global_load_lds_dwordx4 v168, vcc
	s_mov_b32 m0, s60
	s_nop 0
	global_load_lds_dwordx4 v162, s[52:53]
	s_mov_b32 m0, s61
	s_nop 0
	global_load_lds_dwordx4 v166, s[52:53]
	s_waitcnt vmcnt(8)
	s_waitcnt lgkmcnt(0)
	s_barrier
; #define PG8_STAGE(bufoff, gbase, voff) do { _Pragma("unroll") for (int _i = 0; _i < 2; ++_i) \
;         __builtin_amdgcn_global_load_lds((const unsigned*)((const char*)(gbase) + (voff)[_i]), (PG8_LAS unsigned*)(lds + (bufoff) + ldsw + _i * 8192), 16, 0, 0); } while (0)
; #define PG8_LDA(dst, b, h) do { _Pragma("unroll") for (int m = 0; m < 4; ++m) _Pragma("unroll") for (int k = 0; k < 2; ++k) dst[m][k] = *(const PG8_LAS bf16x8*)(lds + PG8_SA(b, h) + aoff + m * 2048 + k * 1024); } while (0)
; #define PG8_LDB(dst, b, h) do { _Pragma("unroll") for (int n = 0; n < 2; ++n) _Pragma("unroll") for (int k = 0; k < 2; ++k) dst[n][k] = *(const PG8_LAS bf16x8*)(lds + PG8_SB(b, h) + boff + n * 2048 + k * 1024); } while (0)
; #define PG8_MMA(ai, bj, At, Bt) do { __builtin_amdgcn_s_setprio(1); _Pragma("unroll") for (int m = 0; m < 4; ++m) _Pragma("unroll") for (int n = 0; n < 2; ++n) _Pragma("unroll") for (int k = 0; k < 2; ++k) \
;         acc[ai][bj][m][n] = __builtin_amdgcn_mfma_f32_16x16x32_bf16(Bt[n][k], At[m][k], acc[ai][bj][m][n], 0, 0, 0); __builtin_amdgcn_s_setprio(0); } while (0)
; #define PG8_WAIT_V(n) asm volatile("s_waitcnt vmcnt(" #n ")" ::: "memory")
; #define PG8_WAIT_L(n) asm volatile("s_waitcnt lgkmcnt(" #n ")" ::: "memory")
; #define PG8_BAR __builtin_amdgcn_s_barrier()
; #define PG8_SCHED __builtin_amdgcn_sched_barrier(0)
; template <class Epi, class Sched, bool ALIGN_EPI = false, bool SP2 = false>
; __device__ __forceinline__ void gemm_phase(PG8_LAS unsigned char* lds, const Gemm g, const Sched& S, const Epi& E, const int tid_in) {
;     ...
;             PG8_WAIT_V(8); PG8_WAIT_L(0); PG8_BAR; PG8_MMA(1, 0, At, B0); PG8_MMA(1, 1, At, B1); PG8_BAR; PG8_SCHED;
;             PG8_LDB(B0, 1, 0); PG8_LDB(B1, 1, 1); PG8_SCHED; PG8_LDA(At, 1, 0); PG8_STAGE(PG8_SA(0, 1), a2 + hstep, voffA);
;             PG8_WAIT_V(8); PG8_WAIT_L(0); PG8_BAR; PG8_MMA(0, 0, At, B0); PG8_MMA(0, 1, At, B1); PG8_BAR; PG8_SCHED;
	s_setprio 1
	s_waitcnt lgkmcnt(0)
	v_mfma_f32_16x16x32_bf16 v[62:65], v[134:137], v[184:187], v[62:65]
	v_mfma_f32_16x16x32_bf16 v[58:61], v[142:145], v[184:187], v[58:61]
	v_mfma_f32_16x16x32_bf16 v[46:49], v[134:137], v[192:195], v[46:49]
	v_mfma_f32_16x16x32_bf16 v[42:45], v[142:145], v[192:195], v[42:45]
	v_mfma_f32_16x16x32_bf16 v[30:33], v[134:137], v[200:203], v[30:33]
	v_mfma_f32_16x16x32_bf16 v[26:29], v[142:145], v[200:203], v[26:29]
	v_mfma_f32_16x16x32_bf16 v[14:17], v[134:137], v[208:211], v[14:17]
	v_mfma_f32_16x16x32_bf16 v[10:13], v[142:145], v[208:211], v[10:13]
	v_mfma_f32_16x16x32_bf16 v[62:65], v[138:141], v[188:191], v[62:65]
	v_mfma_f32_16x16x32_bf16 v[58:61], v[146:149], v[188:191], v[58:61]
	v_mfma_f32_16x16x32_bf16 v[46:49], v[138:141], v[196:199], v[46:49]
	v_mfma_f32_16x16x32_bf16 v[42:45], v[146:149], v[196:199], v[42:45]
	v_mfma_f32_16x16x32_bf16 v[30:33], v[138:141], v[204:207], v[30:33]
	v_mfma_f32_16x16x32_bf16 v[26:29], v[146:149], v[204:207], v[26:29]
	v_mfma_f32_16x16x32_bf16 v[14:17], v[138:141], v[212:215], v[14:17]
	v_mfma_f32_16x16x32_bf16 v[10:13], v[146:149], v[212:215], v[10:13]
	s_setprio 0
	s_setprio 1
	v_mfma_f32_16x16x32_bf16 v[54:57], v[150:153], v[184:187], v[54:57]
	v_mfma_f32_16x16x32_bf16 v[50:53], v[158:161], v[184:187], v[50:53]
	v_mfma_f32_16x16x32_bf16 v[38:41], v[150:153], v[192:195], v[38:41]
	v_mfma_f32_16x16x32_bf16 v[34:37], v[158:161], v[192:195], v[34:37]
	v_mfma_f32_16x16x32_bf16 v[22:25], v[150:153], v[200:203], v[22:25]
	v_mfma_f32_16x16x32_bf16 v[18:21], v[158:161], v[200:203], v[18:21]
	v_mfma_f32_16x16x32_bf16 v[6:9], v[150:153], v[208:211], v[6:9]
	v_mfma_f32_16x16x32_bf16 v[2:5], v[158:161], v[208:211], v[2:5]
	v_mfma_f32_16x16x32_bf16 v[54:57], v[154:157], v[188:191], v[54:57]
	v_mfma_f32_16x16x32_bf16 v[50:53], v[180:183], v[188:191], v[50:53]
	v_mfma_f32_16x16x32_bf16 v[38:41], v[154:157], v[196:199], v[38:41]
	v_mfma_f32_16x16x32_bf16 v[34:37], v[180:183], v[196:199], v[34:37]
	v_mfma_f32_16x16x32_bf16 v[22:25], v[154:157], v[204:207], v[22:25]
	v_mfma_f32_16x16x32_bf16 v[18:21], v[180:183], v[204:207], v[18:21]
	v_mfma_f32_16x16x32_bf16 v[6:9], v[154:157], v[212:215], v[6:9]
	v_mfma_f32_16x16x32_bf16 v[2:5], v[180:183], v[212:215], v[2:5]
	s_setprio 0
	s_barrier
	s_add_i32 s16, 0, 0x18000
	v_add_u32_e32 v0, s16, v177
	s_add_i32 s17, 0, 0x1c000
	ds_read_b128 v[134:137], v0
	ds_read_b128 v[138:141], v0 offset:1024
	ds_read_b128 v[142:145], v0 offset:2048
	ds_read_b128 v[146:149], v0 offset:3072
	v_add_u32_e32 v0, s17, v177
	ds_read_b128 v[150:153], v0
	ds_read_b128 v[154:157], v0 offset:1024
	ds_read_b128 v[158:161], v0 offset:2048
	ds_read_b128 v[180:183], v0 offset:3072
	s_add_u32 s52, s52, s82
	s_addc_u32 s53, s53, 0
	s_mov_b32 m0, s62
	ds_read_b128 v[184:187], v179 offset:32768
	ds_read_b128 v[188:191], v179 offset:33792
	ds_read_b128 v[192:195], v179 offset:34816
	ds_read_b128 v[196:199], v179 offset:35840
	ds_read_b128 v[200:203], v179 offset:36864
	ds_read_b128 v[204:207], v179 offset:37888
	ds_read_b128 v[208:211], v179 offset:38912
	ds_read_b128 v[212:215], v179 offset:39936
	global_load_lds_dwordx4 v162, s[52:53]
	s_mov_b32 m0, s63
	s_nop 0
	global_load_lds_dwordx4 v166, s[52:53]
	s_waitcnt vmcnt(8)
	s_waitcnt lgkmcnt(0)
	s_barrier
	s_setprio 1
	s_waitcnt lgkmcnt(0)
	v_mfma_f32_16x16x32_bf16 v[126:129], v[134:137], v[184:187], v[126:129]
	v_mfma_f32_16x16x32_bf16 v[122:125], v[142:145], v[184:187], v[122:125]
	v_mfma_f32_16x16x32_bf16 v[110:113], v[134:137], v[192:195], v[110:113]
	v_mfma_f32_16x16x32_bf16 v[106:109], v[142:145], v[192:195], v[106:109]
	v_mfma_f32_16x16x32_bf16 v[94:97], v[134:137], v[200:203], v[94:97]
	v_mfma_f32_16x16x32_bf16 v[90:93], v[142:145], v[200:203], v[90:93]
	v_mfma_f32_16x16x32_bf16 v[78:81], v[134:137], v[208:211], v[78:81]
	v_mfma_f32_16x16x32_bf16 v[74:77], v[142:145], v[208:211], v[74:77]
	v_mfma_f32_16x16x32_bf16 v[126:129], v[138:141], v[188:191], v[126:129]
	v_mfma_f32_16x16x32_bf16 v[122:125], v[146:149], v[188:191], v[122:125]
	v_mfma_f32_16x16x32_bf16 v[110:113], v[138:141], v[196:199], v[110:113]
	v_mfma_f32_16x16x32_bf16 v[106:109], v[146:149], v[196:199], v[106:109]
	v_mfma_f32_16x16x32_bf16 v[94:97], v[138:141], v[204:207], v[94:97]
	v_mfma_f32_16x16x32_bf16 v[90:93], v[146:149], v[204:207], v[90:93]
	v_mfma_f32_16x16x32_bf16 v[78:81], v[138:141], v[212:215], v[78:81]
	v_mfma_f32_16x16x32_bf16 v[74:77], v[146:149], v[212:215], v[74:77]
	s_setprio 0
	s_setprio 1
	v_mfma_f32_16x16x32_bf16 v[118:121], v[150:153], v[184:187], v[118:121]
	v_mfma_f32_16x16x32_bf16 v[114:117], v[158:161], v[184:187], v[114:117]
	v_mfma_f32_16x16x32_bf16 v[102:105], v[150:153], v[192:195], v[102:105]
	v_mfma_f32_16x16x32_bf16 v[98:101], v[158:161], v[192:195], v[98:101]
	v_mfma_f32_16x16x32_bf16 v[86:89], v[150:153], v[200:203], v[86:89]
	v_mfma_f32_16x16x32_bf16 v[82:85], v[158:161], v[200:203], v[82:85]
	v_mfma_f32_16x16x32_bf16 v[70:73], v[150:153], v[208:211], v[70:73]
	v_mfma_f32_16x16x32_bf16 v[66:69], v[158:161], v[208:211], v[66:69]
	v_mfma_f32_16x16x32_bf16 v[118:121], v[154:157], v[188:191], v[118:121]
	v_mfma_f32_16x16x32_bf16 v[114:117], v[180:183], v[188:191], v[114:117]
	v_mfma_f32_16x16x32_bf16 v[102:105], v[154:157], v[196:199], v[102:105]
	v_mfma_f32_16x16x32_bf16 v[98:101], v[180:183], v[196:199], v[98:101]
	v_mfma_f32_16x16x32_bf16 v[86:89], v[154:157], v[204:207], v[86:89]
	v_mfma_f32_16x16x32_bf16 v[82:85], v[180:183], v[204:207], v[82:85]
	v_mfma_f32_16x16x32_bf16 v[70:73], v[154:157], v[212:215], v[70:73]
	v_mfma_f32_16x16x32_bf16 v[66:69], v[180:183], v[212:215], v[66:69]
	s_setprio 0
	s_barrier
; #define PG8_STAGE(bufoff, gbase, voff) do { _Pragma("unroll") for (int _i = 0; _i < 2; ++_i) \
;         __builtin_amdgcn_global_load_lds((const unsigned*)((const char*)(gbase) + (voff)[_i]), (PG8_LAS unsigned*)(lds + (bufoff) + ldsw + _i * 8192), 16, 0, 0); } while (0)
; #define PG8_LDA(dst, b, h) do { _Pragma("unroll") for (int m = 0; m < 4; ++m) _Pragma("unroll") for (int k = 0; k < 2; ++k) dst[m][k] = *(const PG8_LAS bf16x8*)(lds + PG8_SA(b, h) + aoff + m * 2048 + k * 1024); } while (0)
; #define PG8_MMA(ai, bj, At, Bt) do { __builtin_amdgcn_s_setprio(1); _Pragma("unroll") for (int m = 0; m < 4; ++m) _Pragma("unroll") for (int n = 0; n < 2; ++n) _Pragma("unroll") for (int k = 0; k < 2; ++k) \
;         acc[ai][bj][m][n] = __builtin_amdgcn_mfma_f32_16x16x32_bf16(Bt[n][k], At[m][k], acc[ai][bj][m][n], 0, 0, 0); __builtin_amdgcn_s_setprio(0); } while (0)
; #define PG8_WAIT_V(n) asm volatile("s_waitcnt vmcnt(" #n ")" ::: "memory")
; #define PG8_WAIT_L(n) asm volatile("s_waitcnt lgkmcnt(" #n ")" ::: "memory")
; #define PG8_BAR __builtin_amdgcn_s_barrier()
; #define PG8_SCHED __builtin_amdgcn_sched_barrier(0)
; template <class Epi, class Sched, bool ALIGN_EPI = false, bool SP2 = false>
; __device__ __forceinline__ void gemm_phase(PG8_LAS unsigned char* lds, const Gemm g, const Sched& S, const Epi& E, const int tid_in) {
;     ...
;         for (int t = 0; t < nt; t += 2) {
;             const bool last = (t == nt - 2);
;             const char* a1 = cA + (size_t)(t + 1) * kstep;
;             const char* a2 = last ? nA : cA + (size_t)(t + 2) * kstep; const char* b2 = last ? nB : cB + (size_t)(t + 2) * kstep;
;             const char* a3 = a2 + kstep; const char* b3 = b2 + kstep;
;     ...
;             PG8_LDA(At, 1, 1); PG8_STAGE(PG8_SB(1, 0), b3, voffB); PG8_STAGE(PG8_SB(1, 1), b3 + hstep, voffB); PG8_STAGE(PG8_SA(1, 0), a3, voffA);
;             PG8_WAIT_V(8); PG8_WAIT_L(0); PG8_BAR; PG8_MMA(1, 0, At, B0); PG8_MMA(1, 1, At, B1); PG8_BAR; PG8_SCHED;
	s_add_i32 s16, s16, s59
	s_mov_b32 m0, s16
	ds_read_b128 v[184:187], v179 offset:49152
	ds_read_b128 v[188:191], v179 offset:50176
	ds_read_b128 v[192:195], v179 offset:51200
	ds_read_b128 v[196:199], v179 offset:52224
	ds_read_b128 v[200:203], v179 offset:53248
	ds_read_b128 v[204:207], v179 offset:54272
	ds_read_b128 v[208:211], v179 offset:55296
	ds_read_b128 v[212:215], v179 offset:56320
	global_load_lds_dwordx4 v164, s[98:99]
	s_add_i32 m0, s16, 0x2000
	s_add_i32 s16, s17, s59
	global_load_lds_dwordx4 v168, s[98:99]
	s_add_u32 vcc_lo, vcc_lo, 0x80
	s_addc_u32 vcc_hi, vcc_hi, 0
	s_mov_b32 m0, s16
	s_nop 0
	global_load_lds_dwordx4 v164, vcc
	s_add_i32 m0, s16, 0x2000
	s_nop 0
	global_load_lds_dwordx4 v168, vcc
	s_mov_b32 m0, s66
	s_nop 0
	global_load_lds_dwordx4 v162, s[100:101]
	s_mov_b32 m0, s67
	s_nop 0
	global_load_lds_dwordx4 v166, s[100:101]
	s_waitcnt vmcnt(8)
	s_waitcnt lgkmcnt(0)
	s_barrier
	s_setprio 1
	s_waitcnt lgkmcnt(0)
	v_mfma_f32_16x16x32_bf16 v[62:65], v[134:137], v[184:187], v[62:65]
	v_mfma_f32_16x16x32_bf16 v[58:61], v[142:145], v[184:187], v[58:61]
	v_mfma_f32_16x16x32_bf16 v[46:49], v[134:137], v[192:195], v[46:49]
	v_mfma_f32_16x16x32_bf16 v[42:45], v[142:145], v[192:195], v[42:45]
	v_mfma_f32_16x16x32_bf16 v[30:33], v[134:137], v[200:203], v[30:33]
	v_mfma_f32_16x16x32_bf16 v[26:29], v[142:145], v[200:203], v[26:29]
	v_mfma_f32_16x16x32_bf16 v[14:17], v[134:137], v[208:211], v[14:17]
	v_mfma_f32_16x16x32_bf16 v[10:13], v[142:145], v[208:211], v[10:13]
	v_mfma_f32_16x16x32_bf16 v[62:65], v[138:141], v[188:191], v[62:65]
	v_mfma_f32_16x16x32_bf16 v[58:61], v[146:149], v[188:191], v[58:61]
	v_mfma_f32_16x16x32_bf16 v[46:49], v[138:141], v[196:199], v[46:49]
	v_mfma_f32_16x16x32_bf16 v[42:45], v[146:149], v[196:199], v[42:45]
	v_mfma_f32_16x16x32_bf16 v[30:33], v[138:141], v[204:207], v[30:33]
	v_mfma_f32_16x16x32_bf16 v[26:29], v[146:149], v[204:207], v[26:29]
	v_mfma_f32_16x16x32_bf16 v[14:17], v[138:141], v[212:215], v[14:17]
	v_mfma_f32_16x16x32_bf16 v[10:13], v[146:149], v[212:215], v[10:13]
	s_setprio 0
	s_setprio 1
	v_mfma_f32_16x16x32_bf16 v[54:57], v[150:153], v[184:187], v[54:57]
	v_mfma_f32_16x16x32_bf16 v[50:53], v[158:161], v[184:187], v[50:53]
	v_mfma_f32_16x16x32_bf16 v[38:41], v[150:153], v[192:195], v[38:41]
	v_mfma_f32_16x16x32_bf16 v[34:37], v[158:161], v[192:195], v[34:37]
	v_mfma_f32_16x16x32_bf16 v[22:25], v[150:153], v[200:203], v[22:25]
	v_mfma_f32_16x16x32_bf16 v[18:21], v[158:161], v[200:203], v[18:21]
	v_mfma_f32_16x16x32_bf16 v[6:9], v[150:153], v[208:211], v[6:9]
	v_mfma_f32_16x16x32_bf16 v[2:5], v[158:161], v[208:211], v[2:5]
	v_mfma_f32_16x16x32_bf16 v[54:57], v[154:157], v[188:191], v[54:57]
	v_mfma_f32_16x16x32_bf16 v[50:53], v[180:183], v[188:191], v[50:53]
	v_mfma_f32_16x16x32_bf16 v[38:41], v[154:157], v[196:199], v[38:41]
	v_mfma_f32_16x16x32_bf16 v[34:37], v[180:183], v[196:199], v[34:37]
	v_mfma_f32_16x16x32_bf16 v[22:25], v[154:157], v[204:207], v[22:25]
	v_mfma_f32_16x16x32_bf16 v[18:21], v[180:183], v[204:207], v[18:21]
	v_mfma_f32_16x16x32_bf16 v[6:9], v[154:157], v[212:215], v[6:9]
	v_mfma_f32_16x16x32_bf16 v[2:5], v[180:183], v[212:215], v[2:5]
	s_add_u32 s10, s10, 0x100
	s_addc_u32 s11, s11, 0
	v_add_u32_e32 v132, 0x100, v132
	v_add_u32_e32 v130, 0x100, v130
	s_add_u32 vcc_lo, s2, s10
	s_addc_u32 s53, s3, s11
	s_add_u32 s44, s50, s10
	s_addc_u32 s45, s51, s11
	s_cmp_eq_u32 s68, s77
	s_cselect_b32 s53, s49, s53
	s_cselect_b32 s52, s48, vcc_lo
	s_cselect_b32 vcc_hi, s43, s45
	s_cselect_b32 vcc_lo, s42, s44
	s_add_u32 s98, vcc_lo, 0x80
	s_addc_u32 s99, vcc_hi, 0
	s_add_u32 s100, s52, 0x80
	s_addc_u32 s101, s53, 0
	s_cmp_ge_u32 s77, s65
	s_setprio 0
	s_barrier
	s_cbranch_scc0 .LBB0_115
	s_and_b64 vcc, exec, s[46:47]
	s_cbranch_vccz .LBB0_118
	s_barrier
